# m_dc: the wave pair computing the per-unit normaliser sums rotates with the unit iteration (was always waves 0 and 1)
# speedup vs baseline: 1.0015x; 1.0015x over previous
; DI unsigned pk2(float lo, float hi) { f32x2 v = {lo, hi}; bf16x2_t b = __builtin_convertvector(v, bf16x2_t); return __builtin_bit_cast(unsigned, b); }
; DI float bflo(unsigned u) { return __uint_as_float(u << 16); }
; DI float bfhi(unsigned u) { return __uint_as_float(u & 0xffff0000u); }
; DI float fexp(float x) { return __builtin_amdgcn_exp2f(x * LOG2E); }
; DI void phase_m_dc(int wv, const ArgP a) {
;     ...
;     for (int u = blockIdx.x; u < 1024; u += gridDim.x) {
;         const int c = u >> 2, h = u & 3; const size_t t0 = (size_t)c * 64;
;         const float emax = ML[c * 4 + h] - BL[c * 4 + h];
;         bf16x8 bfr[4];
;         { const bf16_t* vp = KVT + (size_t)(512 + h * 256 + 32 * w + r32) * S + t0 + 8 * hi; const float* gp = GE + (size_t)h * S + t0 + 8 * hi;
; #pragma unroll
;           for (int ks = 0; ks < 4; ++ks) { const u32x4 v = *(const u32x4*)(vp + 16 * ks); const f32x4 e0 = *(const f32x4*)(gp + 16 * ks), e1 = *(const f32x4*)(gp + 16 * ks + 4);
;               u32x4 o; o.x = pk2(bflo(v.x) * fexp(e0[0] - emax), bfhi(v.x) * fexp(e0[1] - emax)); o.y = pk2(bflo(v.y) * fexp(e0[2] - emax), bfhi(v.y) * fexp(e0[3] - emax));
;               o.z = pk2(bflo(v.z) * fexp(e1[0] - emax), bfhi(v.z) * fexp(e1[1] - emax)); o.w = pk2(bflo(v.w) * fexp(e1[2] - emax), bfhi(v.w) * fexp(e1[3] - emax));
;               bfr[ks] = __builtin_bit_cast(bf16x8, o); } }
;         const bf16_t* kp = KVT + (size_t)(h * 128 + r32) * S + t0 + 8 * hi;
;         bf16_t* op = CST + ((size_t)(c * 4 + h) * 256 + 32 * w + r32) * 128 + 8 * hi;
.LBB0_1460:
	s_or_b64 exec, exec, s[0:1]
	s_cmpk_lt_i32 s80, 0x400
	s_mov_b64 s[0:1], s[82:83]
	s_mov_b32 s2, s50
	s_waitcnt lgkmcnt(0)
	v_mov_b32_e32 v0, v192
	s_barrier
	s_cselect_b64 s[6:7], -1, 0
	s_and_b64 vcc, exec, s[6:7]
	v_lshl_add_u32 v30, s2, 6, v0
	s_nop 0
	v_readfirstlane_b32 s2, v30
	s_cbranch_vccz .LBB0_1465
	s_load_dwordx2 s[4:5], s[0:1], 0xe8
	s_movk_i32 s3, 0xffe0
	v_and_b32_e32 v48, 31, v0
	s_load_dword s18, s[88:89], 0x0
	v_mov_b32_e32 v33, 0
	s_waitcnt lgkmcnt(0)
	s_add_u32 s12, s4, 0x1d00000
	s_addc_u32 s13, s5, 0
	s_add_u32 s14, s4, 0x1d01000
	s_addc_u32 s15, s5, 0
	s_add_u32 s16, s4, 0x1c80000
	s_addc_u32 s17, s5, 0
	s_add_u32 s0, s4, 0xbe0b000
	s_addc_u32 s1, s5, 0
	s_ashr_i32 s2, s2, 1
	v_mov_b32_e32 v1, s2
	s_and_b32 s8, s2, 0xffffffe0
	v_bfi_b32 v1, s3, v1, v0
	v_lshrrev_b32_e32 v0, 2, v0
	v_and_b32_e32 v0, 8, v0
	s_ashr_i32 s2, s8, 31
	v_or_b32_e32 v2, s8, v48
	v_mov_b32_e32 v3, s2
	v_lshlrev_b32_e32 v32, 1, v0
	s_movk_i32 s2, 0x80
	v_ashrrev_i32_e32 v31, 31, v30
	v_lshl_add_u64 v[4:5], s[4:5], 0, v[32:33]
	v_cmp_gt_i32_e32 vcc, s2, v30
	v_lshl_add_u64 v[6:7], v[30:31], 2, s[4:5]
	s_mov_b64 s[2:3], 0x1d03000
	v_lshlrev_b64 v[2:3], 8, v[2:3]
	v_lshl_add_u64 v[34:35], v[6:7], 0, s[2:3]
	v_lshl_add_u64 v[2:3], v[4:5], 0, v[2:3]
	s_mov_b64 s[2:3], 0x3e0b000
	v_add_u32_e32 v49, 0x200, v1
	v_lshl_add_u64 v[36:37], v[2:3], 0, s[2:3]
	v_lshlrev_b32_e32 v38, 1, v0
	v_mov_b32_e32 v39, v33
	v_lshlrev_b32_e32 v31, 2, v0
	s_mov_b32 s19, 0x100000
	s_mov_b32 s20, 0x200000
	s_mov_b32 s21, 0x300000
	s_mov_b32 s2, s80
	s_mov_b32 s90, 0
	s_mov_b32 s92, s2
	s_ashr_i32 s93, s92, 2
	s_and_b32 s94, s92, 3
	s_lshl_b32 s95, s92, 2
	s_add_u32 s96, s14, s95
	s_addc_u32 s97, s15, 0
	s_add_u32 s98, s12, s95
	s_addc_u32 s99, s13, 0
	s_lshl_b32 s84, s93, 7
	s_mov_b32 s85, 0
	s_lshl_b32 s95, s94, 16
	s_add_u32 s86, s16, s95
	s_addc_u32 s87, s17, 0
	s_lshl_b32 s95, s93, 8
	s_add_u32 s86, s86, s95
	s_addc_u32 s87, s87, 0
	v_lshl_add_u32 v248, s94, 8, v49
	v_ashrrev_i32_e32 v249, 31, v248
	v_lshlrev_b64 v[248:249], 15, v[248:249]
	v_lshl_add_u64 v[248:249], s[0:1], 0, v[248:249]
	v_lshl_add_u64 v[248:249], v[248:249], 0, s[84:85]
	v_lshl_add_u64 v[248:249], v[248:249], 0, v[38:39]
	global_load_dword v241, v33, s[96:97]
	global_load_dword v242, v33, s[98:99]
	global_load_dwordx4 v[188:191], v[248:249], off
	global_load_dwordx4 v[200:203], v[248:249], off offset:32
	global_load_dwordx4 v[220:223], v[248:249], off offset:64
	global_load_dwordx4 v[224:227], v[248:249], off offset:96
	global_load_dwordx4 v[204:207], v31, s[86:87]
	global_load_dwordx4 v[208:211], v31, s[86:87] offset:16
	global_load_dwordx4 v[212:215], v31, s[86:87] offset:64
	global_load_dwordx4 v[216:219], v31, s[86:87] offset:80
	global_load_dwordx4 v[228:231], v31, s[86:87] offset:144
	global_load_dwordx4 v[232:235], v31, s[86:87] offset:128
	global_load_dwordx4 v[236:239], v31, s[86:87] offset:208
	global_load_dwordx4 v[244:247], v31, s[86:87] offset:192
	s_waitcnt vmcnt(0)
	s_branch .LBB0_1463
.LBB0_1462:
	s_or_b64 exec, exec, s[4:5]
	s_add_i32 s90, s90, 1
	s_waitcnt vmcnt(8)
	s_add_i32 s2, s2, s18
	s_cmpk_lt_i32 s2, 0x400
	s_cbranch_scc0 .LBB0_1465
.LBB0_1463:
	s_ashr_i32 s10, s2, 2
	s_ashr_i32 s3, s2, 31
	s_and_b32 s22, s2, 3
	s_ashr_i32 s11, s10, 31
	s_lshl_b64 s[4:5], s[2:3], 2
	s_add_u32 s8, s14, s4
	s_addc_u32 s9, s15, s5
	s_add_u32 s4, s12, s4
	s_addc_u32 s5, s13, s5
	v_mov_b32_e32 v32, v241
	v_mov_b32_e32 v40, v242
	v_lshl_add_u32 v0, s22, 8, v49
	v_ashrrev_i32_e32 v1, 31, v0
	v_lshlrev_b64 v[0:1], 15, v[0:1]
	v_lshl_add_u64 v[0:1], s[0:1], 0, v[0:1]
	s_lshl_b64 s[4:5], s[10:11], 7
	s_lshl_b32 s8, s22, 16
	v_lshl_add_u64 v[0:1], v[0:1], 0, s[4:5]
	s_add_u32 s23, s16, s8
	v_lshl_add_u64 v[12:13], v[0:1], 0, v[38:39]
	s_addc_u32 s24, s17, 0
	s_lshl_b64 s[8:9], s[10:11], 8
	v_mov_b64_e32 v[18:19], v[188:189]
	v_mov_b64_e32 v[20:21], v[190:191]
	v_mov_b64_e32 v[0:1], v[200:201]
	v_mov_b64_e32 v[2:3], v[202:203]
	s_add_u32 s8, s23, s8
	s_addc_u32 s9, s24, s9
	v_mov_b64_e32 v[22:23], v[204:205]
	v_mov_b64_e32 v[24:25], v[206:207]
	v_mov_b64_e32 v[26:27], v[208:209]
	v_mov_b64_e32 v[28:29], v[210:211]
	v_mov_b64_e32 v[52:53], v[212:213]
	v_mov_b64_e32 v[54:55], v[214:215]
	v_mov_b64_e32 v[8:9], v[216:217]
	v_mov_b64_e32 v[10:11], v[218:219]
	v_mov_b64_e32 v[4:5], v[220:221]
	v_mov_b64_e32 v[6:7], v[222:223]
	v_mov_b64_e32 v[14:15], v[224:225]
	v_mov_b64_e32 v[16:17], v[226:227]
	v_mov_b64_e32 v[56:57], v[228:229]
	v_mov_b64_e32 v[58:59], v[230:231]
	v_mov_b64_e32 v[60:61], v[232:233]
	v_mov_b64_e32 v[62:63], v[234:235]
	v_mov_b64_e32 v[64:65], v[236:237]
	v_mov_b64_e32 v[66:67], v[238:239]
	v_mov_b64_e32 v[68:69], v[244:245]
	v_mov_b64_e32 v[70:71], v[246:247]
	s_lshl_b32 s22, s22, 7
	v_or_b32_e32 v116, s22, v48
	v_mov_b32_e32 v117, 0
	v_lshlrev_b32_e32 v116, 15, v116
	v_lshl_add_u64 v[118:119], s[0:1], 0, v[116:117]
	v_lshl_add_u64 v[118:119], v[118:119], 0, s[4:5]
	v_lshl_add_u64 v[120:121], v[118:119], 0, v[38:39]
	global_load_dwordx4 v[100:103], v[120:121], off
	global_load_dwordx4 v[104:107], v[120:121], off offset:32
	global_load_dwordx4 v[108:111], v[120:121], off offset:64
	global_load_dwordx4 v[112:115], v[120:121], off offset:96
	v_add_co_u32_e64 v122, s[26:27], s19, v120
	s_nop 1
	v_addc_co_u32_e64 v123, s[26:27], 0, v121, s[26:27]
	global_load_dwordx4 v[140:143], v[122:123], off
	global_load_dwordx4 v[144:147], v[122:123], off offset:32
	global_load_dwordx4 v[148:151], v[122:123], off offset:64
	global_load_dwordx4 v[152:155], v[122:123], off offset:96
	v_add_co_u32_e64 v122, s[26:27], s20, v120
	s_nop 1
	v_addc_co_u32_e64 v123, s[26:27], 0, v121, s[26:27]
; DI unsigned pk2(float lo, float hi) { f32x2 v = {lo, hi}; bf16x2_t b = __builtin_convertvector(v, bf16x2_t); return __builtin_bit_cast(unsigned, b); }
; DI float bflo(unsigned u) { return __uint_as_float(u << 16); }
; DI float bfhi(unsigned u) { return __uint_as_float(u & 0xffff0000u); }
; DI float fexp(float x) { return __builtin_amdgcn_exp2f(x * LOG2E); }
; DI void phase_m_dc(int wv, const ArgP a) {
;     ...
;         { const bf16_t* vp = KVT + (size_t)(512 + h * 256 + 32 * w + r32) * S + t0 + 8 * hi; const float* gp = GE + (size_t)h * S + t0 + 8 * hi;
; #pragma unroll
;           for (int ks = 0; ks < 4; ++ks) { const u32x4 v = *(const u32x4*)(vp + 16 * ks); const f32x4 e0 = *(const f32x4*)(gp + 16 * ks), e1 = *(const f32x4*)(gp + 16 * ks + 4);
;               u32x4 o; o.x = pk2(bflo(v.x) * fexp(e0[0] - emax), bfhi(v.x) * fexp(e0[1] - emax)); o.y = pk2(bflo(v.y) * fexp(e0[2] - emax), bfhi(v.y) * fexp(e0[3] - emax));
;               o.z = pk2(bflo(v.z) * fexp(e1[0] - emax), bfhi(v.z) * fexp(e1[1] - emax)); o.w = pk2(bflo(v.w) * fexp(e1[2] - emax), bfhi(v.w) * fexp(e1[3] - emax));
;               bfr[ks] = __builtin_bit_cast(bf16x8, o); } }
;         const bf16_t* kp = KVT + (size_t)(h * 128 + r32) * S + t0 + 8 * hi;
	global_load_dwordx4 v[156:159], v[122:123], off
	global_load_dwordx4 v[160:163], v[122:123], off offset:32
	global_load_dwordx4 v[164:167], v[122:123], off offset:64
	global_load_dwordx4 v[168:171], v[122:123], off offset:96
	v_add_co_u32_e64 v122, s[26:27], s21, v120
	s_nop 1
	v_addc_co_u32_e64 v123, s[26:27], 0, v121, s[26:27]
	global_load_dwordx4 v[172:175], v[122:123], off
	global_load_dwordx4 v[176:179], v[122:123], off offset:32
	global_load_dwordx4 v[180:183], v[122:123], off offset:64
	global_load_dwordx4 v[184:187], v[122:123], off offset:96
	s_add_i32 s92, s2, s18
	s_cmpk_lt_i32 s92, 0x400
	s_cselect_b32 s92, s92, s2
	s_ashr_i32 s93, s92, 2
	s_and_b32 s94, s92, 3
	s_lshl_b32 s95, s92, 2
	s_add_u32 s96, s14, s95
	s_addc_u32 s97, s15, 0
	s_add_u32 s98, s12, s95
	s_addc_u32 s99, s13, 0
	s_lshl_b32 s84, s93, 7
	s_mov_b32 s85, 0
	s_lshl_b32 s95, s94, 16
	s_add_u32 s86, s16, s95
	s_addc_u32 s87, s17, 0
	s_lshl_b32 s95, s93, 8
	s_add_u32 s86, s86, s95
	s_addc_u32 s87, s87, 0
	v_lshl_add_u32 v248, s94, 8, v49
	v_ashrrev_i32_e32 v249, 31, v248
	v_lshlrev_b64 v[248:249], 15, v[248:249]
	v_lshl_add_u64 v[248:249], s[0:1], 0, v[248:249]
	v_lshl_add_u64 v[248:249], v[248:249], 0, s[84:85]
	v_lshl_add_u64 v[248:249], v[248:249], 0, v[38:39]
	global_load_dword v241, v33, s[96:97]
	global_load_dword v242, v33, s[98:99]
	global_load_dwordx4 v[188:191], v[248:249], off
	global_load_dwordx4 v[200:203], v[248:249], off offset:32
	global_load_dwordx4 v[220:223], v[248:249], off offset:64
	global_load_dwordx4 v[224:227], v[248:249], off offset:96
	global_load_dwordx4 v[204:207], v31, s[86:87]
	global_load_dwordx4 v[208:211], v31, s[86:87] offset:16
	global_load_dwordx4 v[212:215], v31, s[86:87] offset:64
	global_load_dwordx4 v[216:219], v31, s[86:87] offset:80
	global_load_dwordx4 v[228:231], v31, s[86:87] offset:144
	global_load_dwordx4 v[232:235], v31, s[86:87] offset:128
	global_load_dwordx4 v[236:239], v31, s[86:87] offset:208
	global_load_dwordx4 v[244:247], v31, s[86:87] offset:192
	v_sub_f32_e32 v50, v32, v40
	v_sub_f32_e32 v24, v24, v50
	v_sub_f32_e32 v25, v25, v50
	v_sub_f32_e32 v32, v52, v50
	v_sub_f32_e32 v51, v53, v50
	v_sub_f32_e32 v52, v54, v50
	v_sub_f32_e32 v53, v55, v50
	v_sub_f32_e32 v22, v22, v50
	v_sub_f32_e32 v23, v23, v50
	v_mul_f32_e32 v24, 0x3fb8aa3b, v24
	v_mul_f32_e32 v25, 0x3fb8aa3b, v25
	v_mul_f32_e32 v54, 0x3fb8aa3b, v52
	v_mul_f32_e32 v55, 0x3fb8aa3b, v53
	v_mul_f32_e32 v22, 0x3fb8aa3b, v22
	v_mul_f32_e32 v23, 0x3fb8aa3b, v23
	v_exp_f32_e32 v24, v24
	v_exp_f32_e32 v25, v25
	v_exp_f32_e32 v54, v54
	v_exp_f32_e32 v55, v55
	v_exp_f32_e32 v22, v22
	v_exp_f32_e32 v23, v23
	v_lshlrev_b32_e32 v12, 16, v18
	v_and_b32_e32 v13, 0xffff0000, v18
	v_lshlrev_b32_e32 v18, 16, v19
	v_and_b32_e32 v19, 0xffff0000, v19
	v_lshlrev_b32_e32 v72, 16, v0
	v_and_b32_e32 v73, 0xffff0000, v0
	v_lshlrev_b32_e32 v0, 16, v1
	v_and_b32_e32 v1, 0xffff0000, v1
	v_sub_f32_e32 v26, v26, v50
	v_sub_f32_e32 v27, v27, v50
	v_mul_f32_e32 v26, 0x3fb8aa3b, v26
	v_mul_f32_e32 v27, 0x3fb8aa3b, v27
	v_pk_mul_f32 v[18:19], v[24:25], v[18:19]
	v_pk_mul_f32 v[0:1], v[54:55], v[0:1]
	v_mul_f32_e32 v32, 0x3fb8aa3b, v32
	v_mul_f32_e32 v51, 0x3fb8aa3b, v51
	v_exp_f32_e32 v26, v26
	v_exp_f32_e32 v27, v27
	v_pk_mul_f32 v[12:13], v[22:23], v[12:13]
	v_cvt_pk_bf16_f32 v23, v18, v19
	v_cvt_pk_bf16_f32 v19, v0, v1
	v_or_b32_e32 v0, s22, v48
	v_exp_f32_e32 v52, v32
	v_exp_f32_e32 v53, v51
	v_lshlrev_b32_e32 v32, 15, v0
	v_lshl_add_u64 v[0:1], s[0:1], 0, v[32:33]
	v_lshlrev_b32_e32 v40, 16, v20
	v_and_b32_e32 v41, 0xffff0000, v20
	v_lshl_add_u64 v[0:1], v[0:1], 0, s[4:5]
	v_pk_mul_f32 v[24:25], v[26:27], v[40:41]
	v_lshl_add_u64 v[40:41], v[0:1], 0, v[38:39]
	v_pk_mul_f32 v[26:27], v[52:53], v[72:73]
	v_sub_f32_e32 v8, v8, v50
	v_sub_f32_e32 v1, v9, v50
	v_sub_f32_e32 v28, v28, v50
	v_sub_f32_e32 v29, v29, v50
	v_mul_f32_e32 v0, 0x3fb8aa3b, v8
	v_mul_f32_e32 v1, 0x3fb8aa3b, v1
	v_mul_f32_e32 v28, 0x3fb8aa3b, v28
	v_mul_f32_e32 v29, 0x3fb8aa3b, v29
	v_exp_f32_e32 v0, v0
	v_exp_f32_e32 v1, v1
	v_exp_f32_e32 v28, v28
	v_exp_f32_e32 v29, v29
	v_lshlrev_b32_e32 v8, 16, v2
	v_and_b32_e32 v9, 0xffff0000, v2
	v_sub_f32_e32 v2, v10, v50
	v_mul_f32_e32 v2, 0x3fb8aa3b, v2
	v_lshlrev_b32_e32 v20, 16, v21
	v_and_b32_e32 v21, 0xffff0000, v21
	v_pk_mul_f32 v[0:1], v[0:1], v[8:9]
	v_exp_f32_e32 v8, v2
	v_sub_f32_e32 v2, v11, v50
	v_pk_mul_f32 v[20:21], v[28:29], v[20:21]
	v_mul_f32_e32 v2, 0x3fb8aa3b, v2
	v_cvt_pk_bf16_f32 v24, v24, v25
	v_cvt_pk_bf16_f32 v25, v20, v21
	v_exp_f32_e32 v9, v2
	v_cvt_pk_bf16_f32 v20, v0, v1
	v_lshlrev_b32_e32 v0, 16, v3
	v_and_b32_e32 v1, 0xffff0000, v3
	v_sub_f32_e32 v2, v60, v50
	v_sub_f32_e32 v3, v61, v50
	v_mul_f32_e32 v2, 0x3fb8aa3b, v2
	v_mul_f32_e32 v3, 0x3fb8aa3b, v3
	v_exp_f32_e32 v2, v2
	v_exp_f32_e32 v3, v3
	v_pk_mul_f32 v[0:1], v[8:9], v[0:1]
	v_cvt_pk_bf16_f32 v18, v26, v27
	v_cvt_pk_bf16_f32 v21, v0, v1
	v_lshlrev_b32_e32 v0, 16, v4
	v_and_b32_e32 v1, 0xffff0000, v4
	v_pk_mul_f32 v[0:1], v[2:3], v[0:1]
	v_sub_f32_e32 v2, v62, v50
	v_sub_f32_e32 v3, v63, v50
	v_mul_f32_e32 v2, 0x3fb8aa3b, v2
	v_mul_f32_e32 v3, 0x3fb8aa3b, v3
	v_exp_f32_e32 v2, v2
	v_exp_f32_e32 v3, v3
	v_cvt_pk_bf16_f32 v26, v0, v1
	v_lshlrev_b32_e32 v0, 16, v5
	v_and_b32_e32 v1, 0xffff0000, v5
	v_pk_mul_f32 v[0:1], v[2:3], v[0:1]
	v_sub_f32_e32 v2, v56, v50
	v_sub_f32_e32 v3, v57, v50
	v_mul_f32_e32 v2, 0x3fb8aa3b, v2
	v_mul_f32_e32 v3, 0x3fb8aa3b, v3
	v_exp_f32_e32 v2, v2
	v_exp_f32_e32 v3, v3
	v_cvt_pk_bf16_f32 v27, v0, v1
	v_lshlrev_b32_e32 v0, 16, v6
	v_and_b32_e32 v1, 0xffff0000, v6
	v_pk_mul_f32 v[0:1], v[2:3], v[0:1]
	v_sub_f32_e32 v2, v58, v50
	v_sub_f32_e32 v3, v59, v50
	v_mul_f32_e32 v2, 0x3fb8aa3b, v2
	v_mul_f32_e32 v3, 0x3fb8aa3b, v3
	v_exp_f32_e32 v2, v2
	v_exp_f32_e32 v3, v3
	v_cvt_pk_bf16_f32 v28, v0, v1
	v_lshlrev_b32_e32 v0, 16, v7
	v_and_b32_e32 v1, 0xffff0000, v7
	v_pk_mul_f32 v[0:1], v[2:3], v[0:1]
	v_sub_f32_e32 v2, v68, v50
	v_sub_f32_e32 v3, v69, v50
	v_mul_f32_e32 v2, 0x3fb8aa3b, v2
	v_mul_f32_e32 v3, 0x3fb8aa3b, v3
	v_exp_f32_e32 v2, v2
	v_exp_f32_e32 v3, v3
	v_cvt_pk_bf16_f32 v29, v0, v1
	v_lshlrev_b32_e32 v0, 16, v14
	v_and_b32_e32 v1, 0xffff0000, v14
	v_pk_mul_f32 v[0:1], v[2:3], v[0:1]
	v_sub_f32_e32 v2, v70, v50
	v_sub_f32_e32 v3, v71, v50
	v_mul_f32_e32 v2, 0x3fb8aa3b, v2
	v_mul_f32_e32 v3, 0x3fb8aa3b, v3
	v_exp_f32_e32 v2, v2
	v_exp_f32_e32 v3, v3
	v_cvt_pk_bf16_f32 v56, v0, v1
	v_lshlrev_b32_e32 v0, 16, v15
	v_and_b32_e32 v1, 0xffff0000, v15
	v_cvt_pk_bf16_f32 v22, v12, v13
	v_pk_mul_f32 v[0:1], v[2:3], v[0:1]
	v_sub_f32_e32 v32, v64, v50
	v_cvt_pk_bf16_f32 v57, v0, v1
	s_waitcnt vmcnt(29)
; DI unsigned pk2(float lo, float hi) { f32x2 v = {lo, hi}; bf16x2_t b = __builtin_convertvector(v, bf16x2_t); return __builtin_bit_cast(unsigned, b); }
; DI void phase_m_dc(int wv, const ArgP a) {
;     ...
; #pragma unroll
;         for (int rb = 0; rb < 4; ++rb) { f32x16 acc = {};
; #pragma unroll
;             for (int ks = 0; ks < 4; ++ks) { const bf16x8 ka = *(const bf16x8*)(kp + (size_t)(32 * rb) * S + 16 * ks); acc = __builtin_amdgcn_mfma_f32_32x32x16_bf16(ka, bfr[ks], acc, 0, 0, 0); }
; #pragma unroll
;             for (int p = 0; p < 2; ++p) {
;                 const unsigned a0 = pk2(acc[8 * p], acc[8 * p + 1]), a1 = pk2(acc[8 * p + 2], acc[8 * p + 3]), b0 = pk2(acc[8 * p + 4], acc[8 * p + 5]), b1 = pk2(acc[8 * p + 6], acc[8 * p + 7]);
;                 const auto r0 = __builtin_amdgcn_permlane32_swap(a0, b0, false, false), r1 = __builtin_amdgcn_permlane32_swap(a1, b1, false, false);
;                 *(u32x4*)(op + 32 * rb + 16 * p) = (u32x4){r0[0], r1[0], r0[1], r1[1]}; } }
;         if (tid < 128) { const bf16_t* kr = KVT + (size_t)(h * 128 + tid) * S + t0; const float* gp = GE + (size_t)h * S + t0; float s = 0.f;
	v_mfma_f32_32x32x16_bf16 v[0:15], v[100:103], v[22:25], 0
	v_mul_f32_e32 v32, 0x3fb8aa3b, v32
	v_exp_f32_e32 v52, v32
	v_sub_f32_e32 v32, v65, v50
	v_mul_f32_e32 v32, 0x3fb8aa3b, v32
	v_exp_f32_e32 v53, v32
	v_lshlrev_b32_e32 v54, 16, v16
	v_and_b32_e32 v55, 0xffff0000, v16
	s_waitcnt vmcnt(28)
	v_mfma_f32_32x32x16_bf16 v[0:15], v[104:107], v[18:21], v[0:15]
	v_sub_f32_e32 v16, v66, v50
	v_mul_f32_e32 v16, 0x3fb8aa3b, v16
	v_mul_f32_e64 v52, v52, v54
	v_mul_f32_e64 v53, v53, v55
	v_exp_f32_e32 v54, v16
	v_sub_f32_e32 v16, v67, v50
	v_mul_f32_e32 v16, 0x3fb8aa3b, v16
	v_exp_f32_e32 v55, v16
	s_waitcnt vmcnt(27)
	v_mfma_f32_32x32x16_bf16 v[0:15], v[108:111], v[26:29], v[0:15]
	v_lshlrev_b32_e32 v16, 16, v17
	v_and_b32_e32 v17, 0xffff0000, v17
	v_mul_f32_e64 v16, v54, v16
	v_mul_f32_e64 v17, v55, v17
	v_cvt_pk_bf16_f32 v58, v52, v53
	v_cvt_pk_bf16_f32 v59, v16, v17
	s_lshl_b64 s[4:5], s[2:3], 16
	v_lshl_add_u64 v[68:69], v[36:37], 0, s[4:5]
	s_waitcnt vmcnt(26)
	v_mfma_f32_32x32x16_bf16 v[0:15], v[112:115], v[56:59], v[0:15]
	v_add_co_u32_e64 v64, s[4:5], s19, v40
	s_nop 1
	v_addc_co_u32_e64 v65, s[4:5], 0, v41, s[4:5]
	v_add_co_u32_e64 v70, s[4:5], s20, v40
	s_nop 6
	v_cvt_pk_bf16_f32 v0, v0, v1
	v_cvt_pk_bf16_f32 v1, v2, v3
	v_cvt_pk_bf16_f32 v2, v4, v5
	v_cvt_pk_bf16_f32 v3, v6, v7
	s_nop 0
	v_permlane32_swap_b32_e32 v0, v2
	v_permlane32_swap_b32_e32 v1, v3
	global_store_dwordx4 v[68:69], v[0:3], off
	v_cvt_pk_bf16_f32 v4, v8, v9
	v_cvt_pk_bf16_f32 v5, v10, v11
	v_cvt_pk_bf16_f32 v6, v12, v13
	v_cvt_pk_bf16_f32 v7, v14, v15
	s_nop 0
	v_permlane32_swap_b32_e32 v4, v6
	v_permlane32_swap_b32_e32 v5, v7
	global_store_dwordx4 v[68:69], v[4:7], off offset:32
	v_addc_co_u32_e64 v71, s[4:5], 0, v41, s[4:5]
	s_waitcnt vmcnt(27)
	v_mfma_f32_32x32x16_bf16 v[2:17], v[140:143], v[22:25], 0
	s_waitcnt vmcnt(26)
	v_mfma_f32_32x32x16_bf16 v[2:17], v[144:147], v[18:21], v[2:17]
	s_waitcnt vmcnt(25)
	v_mfma_f32_32x32x16_bf16 v[2:17], v[148:151], v[26:29], v[2:17]
	s_waitcnt vmcnt(24)
	v_mfma_f32_32x32x16_bf16 v[2:17], v[152:155], v[56:59], v[2:17]
	s_nop 11
	v_cvt_pk_bf16_f32 v0, v2, v3
	v_cvt_pk_bf16_f32 v1, v4, v5
	v_cvt_pk_bf16_f32 v2, v6, v7
	v_cvt_pk_bf16_f32 v3, v8, v9
	s_nop 0
	v_permlane32_swap_b32_e32 v0, v2
	v_permlane32_swap_b32_e32 v1, v3
	global_store_dwordx4 v[68:69], v[0:3], off offset:64
	v_cvt_pk_bf16_f32 v64, v10, v11
	v_cvt_pk_bf16_f32 v65, v12, v13
	v_cvt_pk_bf16_f32 v66, v14, v15
	s_waitcnt vmcnt(24)
	v_mfma_f32_32x32x16_bf16 v[0:15], v[156:159], v[22:25], 0
	v_cvt_pk_bf16_f32 v67, v16, v17
	v_permlane32_swap_b32_e32 v64, v66
	s_nop 0
	v_permlane32_swap_b32_e32 v65, v67
	global_store_dwordx4 v[68:69], v[64:67], off offset:96
	s_waitcnt vmcnt(24)
	v_mfma_f32_32x32x16_bf16 v[0:15], v[160:163], v[18:21], v[0:15]
	v_add_co_u32_e64 v16, s[4:5], s21, v40
	s_nop 1
	v_addc_co_u32_e64 v17, s[4:5], 0, v41, s[4:5]
	s_waitcnt vmcnt(23)
	v_mfma_f32_32x32x16_bf16 v[0:15], v[164:167], v[26:29], v[0:15]
	s_waitcnt vmcnt(22)
	v_mfma_f32_32x32x16_bf16 v[0:15], v[168:171], v[56:59], v[0:15]
	s_nop 11
	v_cvt_pk_bf16_f32 v0, v0, v1
	v_cvt_pk_bf16_f32 v1, v2, v3
	v_cvt_pk_bf16_f32 v2, v4, v5
	v_cvt_pk_bf16_f32 v3, v6, v7
	s_nop 0
	v_permlane32_swap_b32_e32 v0, v2
	v_permlane32_swap_b32_e32 v1, v3
	global_store_dwordx4 v[68:69], v[0:3], off offset:128
	v_cvt_pk_bf16_f32 v4, v8, v9
	v_cvt_pk_bf16_f32 v5, v10, v11
	v_cvt_pk_bf16_f32 v6, v12, v13
	v_cvt_pk_bf16_f32 v7, v14, v15
	s_nop 0
	v_permlane32_swap_b32_e32 v4, v6
	v_permlane32_swap_b32_e32 v5, v7
	global_store_dwordx4 v[68:69], v[4:7], off offset:160
	s_waitcnt vmcnt(23)
	v_mfma_f32_32x32x16_bf16 v[0:15], v[172:175], v[22:25], 0
	s_waitcnt vmcnt(22)
	v_mfma_f32_32x32x16_bf16 v[0:15], v[176:179], v[18:21], v[0:15]
	s_waitcnt vmcnt(21)
	v_mfma_f32_32x32x16_bf16 v[0:15], v[180:183], v[26:29], v[0:15]
	s_waitcnt vmcnt(20)
	v_mfma_f32_32x32x16_bf16 v[0:15], v[184:187], v[56:59], v[0:15]
	s_nop 11
	v_cvt_pk_bf16_f32 v0, v0, v1
	v_cvt_pk_bf16_f32 v1, v2, v3
	v_cvt_pk_bf16_f32 v2, v4, v5
	v_cvt_pk_bf16_f32 v3, v6, v7
	v_cvt_pk_bf16_f32 v4, v8, v9
	v_cvt_pk_bf16_f32 v5, v10, v11
	v_cvt_pk_bf16_f32 v6, v12, v13
	v_cvt_pk_bf16_f32 v7, v14, v15
	v_permlane32_swap_b32_e32 v0, v2
	v_permlane32_swap_b32_e32 v1, v3
	v_permlane32_swap_b32_e32 v4, v6
	v_permlane32_swap_b32_e32 v5, v7
	global_store_dwordx4 v[68:69], v[0:3], off offset:192
	global_store_dwordx4 v[68:69], v[4:7], off offset:224
	s_and_b32 s91, s90, 3
	s_lshl_b32 s91, s91, 7
	v_subrev_u32_e32 v250, s91, v30
	v_and_b32_e32 v250, 0x1ff, v250
	v_cmp_gt_i32_e32 vcc, 0x80, v250
	s_and_saveexec_b64 s[4:5], vcc
	s_cbranch_execz .LBB0_1462
; DI float bflo(unsigned u) { return __uint_as_float(u << 16); }
; DI float bfhi(unsigned u) { return __uint_as_float(u & 0xffff0000u); }
; DI float fexp(float x) { return __builtin_amdgcn_exp2f(x * LOG2E); }
; DI void phase_m_dc(int wv, const ArgP a) {
;     ...
;         if (tid < 128) { const bf16_t* kr = KVT + (size_t)(h * 128 + tid) * S + t0; const float* gp = GE + (size_t)h * S + t0; float s = 0.f;
; #pragma unroll
;             for (int p = 0; p < 8; ++p) { const u32x4 v = *(const u32x4*)(kr + 8 * p); const f32x4 e0 = *(const f32x4*)(gp + 8 * p), e1 = *(const f32x4*)(gp + 8 * p + 4);
;                 s += bflo(v.x) * fexp(e0[0] - emax) + bfhi(v.x) * fexp(e0[1] - emax) + bflo(v.y) * fexp(e0[2] - emax) + bfhi(v.y) * fexp(e0[3] - emax)
;                    + bflo(v.z) * fexp(e1[0] - emax) + bfhi(v.z) * fexp(e1[1] - emax) + bflo(v.w) * fexp(e1[2] - emax) + bfhi(v.w) * fexp(e1[3] - emax); }
	global_load_dwordx4 v[10:13], v33, s[8:9]
	global_load_dwordx4 v[14:17], v33, s[8:9] offset:16
	global_load_dwordx4 v[18:21], v33, s[8:9] offset:32
	global_load_dwordx4 v[22:25], v33, s[8:9] offset:48
	global_load_dwordx4 v[26:29], v33, s[8:9] offset:64
	v_add_u32_e32 v0, s22, v250
	v_ashrrev_i32_e32 v1, 31, v0
	v_lshlrev_b64 v[0:1], 15, v[0:1]
	s_lshl_b64 s[10:11], s[10:11], 6
	v_lshl_add_u64 v[0:1], s[0:1], 0, v[0:1]
	v_lshl_add_u64 v[8:9], s[10:11], 1, v[0:1]
	global_load_dwordx4 v[52:55], v[8:9], off offset:16
	global_load_dwordx4 v[56:59], v[8:9], off
	global_load_dwordx4 v[60:63], v33, s[8:9] offset:80
	global_load_dwordx4 v[64:67], v33, s[8:9] offset:112
	global_load_dwordx4 v[68:71], v33, s[8:9] offset:96
	global_load_dwordx4 v[0:3], v[8:9], off offset:32
	global_load_dwordx4 v[4:7], v[8:9], off offset:48
	s_waitcnt vmcnt(11)
	v_sub_f32_e32 v11, v11, v50
	v_sub_f32_e32 v13, v13, v50
	s_waitcnt vmcnt(9)
	v_sub_f32_e32 v19, v19, v50
	v_sub_f32_e32 v10, v10, v50
	v_sub_f32_e32 v12, v12, v50
	v_sub_f32_e32 v16, v16, v50
	v_sub_f32_e32 v18, v18, v50
	v_mul_f32_e32 v11, 0x3fb8aa3b, v11
	v_mul_f32_e32 v13, 0x3fb8aa3b, v13
	v_mul_f32_e32 v19, 0x3fb8aa3b, v19
	v_sub_f32_e32 v15, v15, v50
	v_sub_f32_e32 v20, v20, v50
	v_mul_f32_e32 v10, 0x3fb8aa3b, v10
	v_mul_f32_e32 v32, 0x3fb8aa3b, v12
	v_mul_f32_e32 v41, 0x3fb8aa3b, v16
	v_mul_f32_e32 v51, 0x3fb8aa3b, v18
	v_exp_f32_e32 v12, v11
	v_exp_f32_e32 v16, v13
	v_exp_f32_e32 v13, v19
	v_sub_f32_e32 v14, v14, v50
	v_sub_f32_e32 v17, v17, v50
	v_sub_f32_e32 v21, v21, v50
	s_waitcnt vmcnt(8)
	v_sub_f32_e32 v23, v23, v50
	v_sub_f32_e32 v24, v24, v50
	v_mul_f32_e32 v15, 0x3fb8aa3b, v15
	v_mul_f32_e32 v72, 0x3fb8aa3b, v20
	v_exp_f32_e32 v10, v10
	v_exp_f32_e32 v11, v51
	v_sub_f32_e32 v22, v22, v50
	v_mul_f32_e32 v40, 0x3fb8aa3b, v14
	v_mul_f32_e32 v17, 0x3fb8aa3b, v17
	v_mul_f32_e32 v21, 0x3fb8aa3b, v21
	v_mul_f32_e32 v23, 0x3fb8aa3b, v23
	v_mul_f32_e32 v74, 0x3fb8aa3b, v24
	v_exp_f32_e32 v14, v32
	v_exp_f32_e32 v20, v15
	v_exp_f32_e32 v15, v72
	v_mul_f32_e32 v73, 0x3fb8aa3b, v22
	v_exp_f32_e32 v24, v17
	v_exp_f32_e32 v17, v21
	v_exp_f32_e32 v21, v23
	v_exp_f32_e32 v23, v74
	s_waitcnt vmcnt(6)
	v_and_b32_e32 v75, 0xffff0000, v52
	s_waitcnt vmcnt(5)
	v_and_b32_e32 v74, 0xffff0000, v56
	v_exp_f32_e32 v18, v40
	v_exp_f32_e32 v19, v73
	v_lshlrev_b32_e32 v73, 16, v52
	v_lshlrev_b32_e32 v72, 16, v56
	v_pk_mul_f32 v[12:13], v[12:13], v[74:75]
	v_sub_f32_e32 v25, v25, v50
	v_lshlrev_b32_e32 v77, 16, v53
	v_lshlrev_b32_e32 v76, 16, v57
	v_pk_fma_f32 v[10:11], v[10:11], v[72:73], v[12:13]
	v_mul_f32_e32 v25, 0x3fb8aa3b, v25
	v_exp_f32_e32 v22, v41
	v_and_b32_e32 v53, 0xffff0000, v53
	v_and_b32_e32 v52, 0xffff0000, v57
	v_pk_fma_f32 v[10:11], v[14:15], v[76:77], v[10:11]
	v_exp_f32_e32 v25, v25
	v_lshlrev_b32_e32 v57, 16, v54
	v_lshlrev_b32_e32 v56, 16, v58
	v_pk_fma_f32 v[10:11], v[16:17], v[52:53], v[10:11]
	v_and_b32_e32 v79, 0xffff0000, v54
	v_and_b32_e32 v78, 0xffff0000, v58
	v_pk_fma_f32 v[10:11], v[18:19], v[56:57], v[10:11]
	v_lshlrev_b32_e32 v81, 16, v55
	v_lshlrev_b32_e32 v80, 16, v59
	v_pk_fma_f32 v[10:11], v[20:21], v[78:79], v[10:11]
	v_and_b32_e32 v55, 0xffff0000, v55
	v_and_b32_e32 v54, 0xffff0000, v59
	v_pk_fma_f32 v[10:11], v[22:23], v[80:81], v[10:11]
	v_sub_f32_e32 v18, v27, v50
	v_pk_fma_f32 v[10:11], v[24:25], v[54:55], v[10:11]
	v_mul_f32_e32 v18, 0x3fb8aa3b, v18
	v_add_f32_e32 v10, 0, v10
	v_add_f32_e32 v32, v10, v11
	global_load_dwordx4 v[10:13], v33, s[8:9] offset:144
	global_load_dwordx4 v[14:17], v33, s[8:9] offset:128
	v_exp_f32_e32 v56, v18
	v_sub_f32_e32 v18, v28, v50
	v_mul_f32_e32 v18, 0x3fb8aa3b, v18
	v_exp_f32_e32 v58, v18
	v_sub_f32_e32 v18, v29, v50
	v_mul_f32_e32 v18, 0x3fb8aa3b, v18
	v_sub_f32_e32 v26, v26, v50
	v_exp_f32_e32 v72, v18
	s_waitcnt vmcnt(6)
	v_sub_f32_e32 v18, v60, v50
	v_mul_f32_e32 v26, 0x3fb8aa3b, v26
	v_mul_f32_e32 v18, 0x3fb8aa3b, v18
	v_exp_f32_e32 v40, v26
	v_exp_f32_e32 v60, v18
	v_sub_f32_e32 v18, v61, v50
	s_waitcnt vmcnt(4)
	v_sub_f32_e32 v26, v69, v50
	v_mul_f32_e32 v18, 0x3fb8aa3b, v18
	v_mul_f32_e32 v26, 0x3fb8aa3b, v26
	v_exp_f32_e32 v74, v18
	v_sub_f32_e32 v18, v62, v50
	v_exp_f32_e32 v57, v26
	v_sub_f32_e32 v26, v70, v50
	v_mul_f32_e32 v18, 0x3fb8aa3b, v18
	v_mul_f32_e32 v26, 0x3fb8aa3b, v26
	v_exp_f32_e32 v62, v18
	v_sub_f32_e32 v18, v63, v50
	v_exp_f32_e32 v59, v26
	v_sub_f32_e32 v26, v71, v50
	v_mul_f32_e32 v18, 0x3fb8aa3b, v18
	v_mul_f32_e32 v26, 0x3fb8aa3b, v26
	v_exp_f32_e32 v76, v18
	v_sub_f32_e32 v18, v68, v50
	v_exp_f32_e32 v73, v26
	v_sub_f32_e32 v26, v64, v50
	v_mul_f32_e32 v18, 0x3fb8aa3b, v18
	v_mul_f32_e32 v26, 0x3fb8aa3b, v26
	v_exp_f32_e32 v41, v18
	global_load_dwordx4 v[18:21], v33, s[8:9] offset:176
	global_load_dwordx4 v[22:25], v33, s[8:9] offset:160
	v_exp_f32_e32 v61, v26
	v_sub_f32_e32 v26, v65, v50
	v_mul_f32_e32 v26, 0x3fb8aa3b, v26
	v_exp_f32_e32 v75, v26
	v_sub_f32_e32 v26, v66, v50
	v_mul_f32_e32 v26, 0x3fb8aa3b, v26
	v_exp_f32_e32 v63, v26
	v_sub_f32_e32 v26, v67, v50
	s_waitcnt vmcnt(4)
; DI float bflo(unsigned u) { return __uint_as_float(u << 16); }
; DI float bfhi(unsigned u) { return __uint_as_float(u & 0xffff0000u); }
; DI float fexp(float x) { return __builtin_amdgcn_exp2f(x * LOG2E); }
; DI void phase_m_dc(int wv, const ArgP a) {
;     ...
;         if (tid < 128) { const bf16_t* kr = KVT + (size_t)(h * 128 + tid) * S + t0; const float* gp = GE + (size_t)h * S + t0; float s = 0.f;
; #pragma unroll
;             for (int p = 0; p < 8; ++p) { const u32x4 v = *(const u32x4*)(kr + 8 * p); const f32x4 e0 = *(const f32x4*)(gp + 8 * p), e1 = *(const f32x4*)(gp + 8 * p + 4);
;                 s += bflo(v.x) * fexp(e0[0] - emax) + bfhi(v.x) * fexp(e0[1] - emax) + bflo(v.y) * fexp(e0[2] - emax) + bfhi(v.y) * fexp(e0[3] - emax)
;                    + bflo(v.z) * fexp(e1[0] - emax) + bfhi(v.z) * fexp(e1[1] - emax) + bflo(v.w) * fexp(e1[2] - emax) + bfhi(v.w) * fexp(e1[3] - emax); }
;             NST[(size_t)(c * 4 + h) * 128 + tid] = s; }
	v_and_b32_e32 v67, 0xffff0000, v4
	v_and_b32_e32 v66, 0xffff0000, v0
	v_lshlrev_b32_e32 v65, 16, v4
	v_lshlrev_b32_e32 v64, 16, v0
	v_pk_mul_f32 v[56:57], v[56:57], v[66:67]
	v_mul_f32_e32 v26, 0x3fb8aa3b, v26
	v_pk_fma_f32 v[40:41], v[40:41], v[64:65], v[56:57]
	v_lshlrev_b32_e32 v57, 16, v5
	v_lshlrev_b32_e32 v56, 16, v1
	v_pk_fma_f32 v[40:41], v[58:59], v[56:57], v[40:41]
	v_and_b32_e32 v5, 0xffff0000, v5
	v_and_b32_e32 v4, 0xffff0000, v1
	v_exp_f32_e32 v77, v26
	v_pk_fma_f32 v[0:1], v[72:73], v[4:5], v[40:41]
	v_lshlrev_b32_e32 v5, 16, v6
	v_lshlrev_b32_e32 v4, 16, v2
	v_pk_fma_f32 v[0:1], v[60:61], v[4:5], v[0:1]
	v_and_b32_e32 v5, 0xffff0000, v6
	v_and_b32_e32 v4, 0xffff0000, v2
	v_pk_fma_f32 v[0:1], v[74:75], v[4:5], v[0:1]
	v_lshlrev_b32_e32 v5, 16, v7
	v_lshlrev_b32_e32 v4, 16, v3
	v_pk_fma_f32 v[0:1], v[62:63], v[4:5], v[0:1]
	v_and_b32_e32 v5, 0xffff0000, v7
	v_and_b32_e32 v4, 0xffff0000, v3
	global_load_dwordx4 v[26:29], v[8:9], off offset:64
	global_load_dwordx4 v[52:55], v[8:9], off offset:80
	v_pk_fma_f32 v[40:41], v[76:77], v[4:5], v[0:1]
	global_load_dwordx4 v[0:3], v33, s[8:9] offset:208
	global_load_dwordx4 v[4:7], v33, s[8:9] offset:192
	global_load_dwordx4 v[56:59], v[8:9], off offset:96
	global_load_dwordx4 v[60:63], v[8:9], off offset:112
	v_add_f32_e32 v32, v32, v40
	v_add_f32_e32 v32, v32, v41
	s_waitcnt vmcnt(9)
	v_sub_f32_e32 v13, v13, v50
	s_waitcnt vmcnt(8)
	v_sub_f32_e32 v8, v14, v50
	v_mul_f32_e32 v8, 0x3fb8aa3b, v8
	v_exp_f32_e32 v40, v8
	v_sub_f32_e32 v8, v15, v50
	v_mul_f32_e32 v8, 0x3fb8aa3b, v8
	v_exp_f32_e32 v64, v8
	v_sub_f32_e32 v8, v16, v50
	v_mul_f32_e32 v8, 0x3fb8aa3b, v8
	v_exp_f32_e32 v66, v8
	v_sub_f32_e32 v8, v17, v50
	v_mul_f32_e32 v8, 0x3fb8aa3b, v8
	v_exp_f32_e32 v68, v8
	v_sub_f32_e32 v8, v10, v50
	v_mul_f32_e32 v8, 0x3fb8aa3b, v8
	v_exp_f32_e32 v70, v8
	v_sub_f32_e32 v8, v11, v50
	v_mul_f32_e32 v8, 0x3fb8aa3b, v8
	v_exp_f32_e32 v72, v8
	global_load_dwordx4 v[8:11], v33, s[8:9] offset:240
	global_load_dwordx4 v[14:17], v33, s[8:9] offset:224
	v_mul_f32_e32 v13, 0x3fb8aa3b, v13
	v_exp_f32_e32 v74, v13
	v_sub_f32_e32 v12, v12, v50
	v_mul_f32_e32 v12, 0x3fb8aa3b, v12
	v_exp_f32_e32 v12, v12
	s_lshl_b64 s[8:9], s[2:3], 9
	s_waitcnt vmcnt(8)
	v_sub_f32_e32 v13, v22, v50
	v_mul_f32_e32 v13, 0x3fb8aa3b, v13
	v_exp_f32_e32 v41, v13
	v_sub_f32_e32 v13, v23, v50
	v_mul_f32_e32 v13, 0x3fb8aa3b, v13
	v_exp_f32_e32 v65, v13
	v_sub_f32_e32 v13, v24, v50
	v_mul_f32_e32 v13, 0x3fb8aa3b, v13
	v_exp_f32_e32 v67, v13
	v_sub_f32_e32 v13, v25, v50
	v_mul_f32_e32 v13, 0x3fb8aa3b, v13
	v_exp_f32_e32 v69, v13
	v_sub_f32_e32 v13, v18, v50
	v_mul_f32_e32 v13, 0x3fb8aa3b, v13
	v_exp_f32_e32 v71, v13
	v_sub_f32_e32 v13, v19, v50
	v_mul_f32_e32 v13, 0x3fb8aa3b, v13
	v_sub_f32_e32 v18, v21, v50
	v_exp_f32_e32 v73, v13
	v_sub_f32_e32 v13, v20, v50
	v_mul_f32_e32 v18, 0x3fb8aa3b, v18
	v_exp_f32_e32 v75, v18
	v_mul_f32_e32 v13, 0x3fb8aa3b, v13
	v_exp_f32_e32 v13, v13
	s_waitcnt vmcnt(7)
	v_and_b32_e32 v20, 0xffff0000, v26
	s_waitcnt vmcnt(6)
	v_and_b32_e32 v21, 0xffff0000, v52
	v_lshlrev_b32_e32 v19, 16, v52
	v_lshlrev_b32_e32 v18, 16, v26
	v_pk_mul_f32 v[20:21], v[64:65], v[20:21]
	s_waitcnt vmcnt(5)
	v_sub_f32_e32 v1, v1, v50
	v_pk_fma_f32 v[18:19], v[40:41], v[18:19], v[20:21]
	v_lshlrev_b32_e32 v21, 16, v53
	v_lshlrev_b32_e32 v20, 16, v27
	v_pk_fma_f32 v[18:19], v[66:67], v[20:21], v[18:19]
	v_and_b32_e32 v21, 0xffff0000, v53
	v_and_b32_e32 v20, 0xffff0000, v27
	v_pk_fma_f32 v[18:19], v[68:69], v[20:21], v[18:19]
	v_lshlrev_b32_e32 v21, 16, v54
	v_lshlrev_b32_e32 v20, 16, v28
	v_pk_fma_f32 v[18:19], v[70:71], v[20:21], v[18:19]
	v_and_b32_e32 v21, 0xffff0000, v54
	v_and_b32_e32 v20, 0xffff0000, v28
	v_pk_fma_f32 v[18:19], v[72:73], v[20:21], v[18:19]
	v_lshlrev_b32_e32 v21, 16, v55
	v_lshlrev_b32_e32 v20, 16, v29
	v_pk_fma_f32 v[12:13], v[12:13], v[20:21], v[18:19]
	v_and_b32_e32 v19, 0xffff0000, v55
	v_and_b32_e32 v18, 0xffff0000, v29
	v_mul_f32_e32 v1, 0x3fb8aa3b, v1
	v_pk_fma_f32 v[12:13], v[74:75], v[18:19], v[12:13]
	s_waitcnt vmcnt(4)
	v_sub_f32_e32 v5, v5, v50
	v_exp_f32_e32 v20, v1
	v_sub_f32_e32 v1, v2, v50
	v_add_f32_e32 v12, v32, v12
	v_mul_f32_e32 v5, 0x3fb8aa3b, v5
	v_mul_f32_e32 v1, 0x3fb8aa3b, v1
	v_add_f32_e32 v24, v12, v13
	v_exp_f32_e32 v12, v5
	v_sub_f32_e32 v5, v6, v50
	v_exp_f32_e32 v2, v1
	v_sub_f32_e32 v1, v3, v50
	v_mul_f32_e32 v5, 0x3fb8aa3b, v5
	v_mul_f32_e32 v1, 0x3fb8aa3b, v1
	v_exp_f32_e32 v6, v5
	v_sub_f32_e32 v5, v7, v50
	v_exp_f32_e32 v22, v1
	s_waitcnt vmcnt(0)
	v_sub_f32_e32 v1, v14, v50
	v_mul_f32_e32 v5, 0x3fb8aa3b, v5
	v_mul_f32_e32 v1, 0x3fb8aa3b, v1
	v_exp_f32_e32 v18, v5
	v_exp_f32_e32 v5, v1
	v_sub_f32_e32 v1, v15, v50
	v_mul_f32_e32 v1, 0x3fb8aa3b, v1
	v_exp_f32_e32 v13, v1
	v_sub_f32_e32 v1, v16, v50
	v_sub_f32_e32 v4, v4, v50
	v_mul_f32_e32 v1, 0x3fb8aa3b, v1
	v_mul_f32_e32 v4, 0x3fb8aa3b, v4
	v_exp_f32_e32 v7, v1
	v_sub_f32_e32 v1, v17, v50
	v_exp_f32_e32 v4, v4
	v_mul_f32_e32 v1, 0x3fb8aa3b, v1
	v_sub_f32_e32 v3, v9, v50
	v_sub_f32_e32 v0, v0, v50
	v_exp_f32_e32 v19, v1
	v_sub_f32_e32 v1, v8, v50
	v_mul_f32_e32 v3, 0x3fb8aa3b, v3
	v_sub_f32_e32 v8, v11, v50
	v_mul_f32_e32 v0, 0x3fb8aa3b, v0
	v_mul_f32_e32 v1, 0x3fb8aa3b, v1
	v_exp_f32_e32 v21, v3
	v_sub_f32_e32 v3, v10, v50
	v_mul_f32_e32 v8, 0x3fb8aa3b, v8
	v_and_b32_e32 v11, 0xffff0000, v60
	v_and_b32_e32 v10, 0xffff0000, v56
	v_exp_f32_e32 v0, v0
	v_exp_f32_e32 v1, v1
	v_exp_f32_e32 v23, v8
	v_lshlrev_b32_e32 v9, 16, v60
	v_lshlrev_b32_e32 v8, 16, v56
	v_pk_mul_f32 v[10:11], v[12:13], v[10:11]
	v_mul_f32_e32 v3, 0x3fb8aa3b, v3
	v_pk_fma_f32 v[4:5], v[4:5], v[8:9], v[10:11]
	v_lshlrev_b32_e32 v9, 16, v61
	v_lshlrev_b32_e32 v8, 16, v57
	v_exp_f32_e32 v3, v3
	v_pk_fma_f32 v[4:5], v[6:7], v[8:9], v[4:5]
	v_and_b32_e32 v7, 0xffff0000, v61
	v_and_b32_e32 v6, 0xffff0000, v57
	v_pk_fma_f32 v[4:5], v[18:19], v[6:7], v[4:5]
	v_lshlrev_b32_e32 v7, 16, v62
	v_lshlrev_b32_e32 v6, 16, v58
	v_pk_fma_f32 v[0:1], v[0:1], v[6:7], v[4:5]
	v_and_b32_e32 v5, 0xffff0000, v62
	v_and_b32_e32 v4, 0xffff0000, v58
	v_pk_fma_f32 v[0:1], v[20:21], v[4:5], v[0:1]
	v_lshlrev_b32_e32 v5, 16, v63
	v_lshlrev_b32_e32 v4, 16, v59
	v_pk_fma_f32 v[0:1], v[2:3], v[4:5], v[0:1]
	v_and_b32_e32 v3, 0xffff0000, v63
	v_and_b32_e32 v2, 0xffff0000, v59
	v_pk_fma_f32 v[0:1], v[22:23], v[2:3], v[0:1]
	s_nop 0
	v_add_f32_e32 v0, v24, v0
	v_add_f32_e32 v2, v0, v1
	v_sub_u32_e32 v252, v250, v30
	v_lshlrev_b32_e32 v252, 2, v252
	v_ashrrev_i32_e32 v253, 31, v252
	v_lshl_add_u64 v[0:1], v[34:35], 0, s[8:9]
	v_lshl_add_u64 v[0:1], v[0:1], 0, v[252:253]
	global_store_dword v[0:1], v2, off
	s_branch .LBB0_1462
